# P0 rmsnorm trip: all 16 row loads issued together (late loads renamed into free registers and hoisted, vmcnt waits regenerated)
# baseline (speedup 1.0000x reference)
.LBB0_15:
	v_lshl_add_u64 v[44:45], v[66:67], 4, s[30:31]
	global_load_dwordx4 v[28:31], v[44:45], off
	global_load_dwordx4 v[24:27], v[44:45], off offset:1024
	global_load_dwordx4 v[20:23], v[44:45], off offset:2048
	global_load_dwordx4 v[16:19], v[44:45], off offset:3072
	v_lshl_add_u64 v[46:47], v[44:45], 0, s[2:3]
	v_add_co_u32_e32 v52, vcc, 0x1000, v44
	v_lshl_add_u64 v[74:75], v[44:45], 0, s[16:17]
	s_nop 0
	v_addc_co_u32_e32 v53, vcc, 0, v45, vcc
	global_load_dwordx4 v[48:51], v[46:47], off offset:1024
	global_load_dwordx4 v[36:39], v[46:47], off offset:2048
	global_load_dwordx4 v[40:43], v[74:75], off offset:1024
	global_load_dwordx4 v[32:35], v[74:75], off offset:2048
	global_load_dwordx4 v[60:63], v[52:53], off
	global_load_dwordx4 v[56:59], v[46:47], off offset:3072
	v_add_co_u32_e32 v54, vcc, 0x2000, v44
	v_lshl_add_u64 v[70:71], v[44:45], 0, s[18:19]
	s_nop 0
	v_addc_co_u32_e32 v55, vcc, 0, v45, vcc
	v_add_co_u32_e32 v76, vcc, 0x3000, v44
	s_nop 1
	v_addc_co_u32_e32 v77, vcc, 0, v45, vcc
	global_load_dwordx4 v[104:107], v[54:55], off
	global_load_dwordx4 v[108:111], v[74:75], off offset:3072
	global_load_dwordx4 v[112:115], v[70:71], off offset:1024
	global_load_dwordx4 v[116:119], v[70:71], off offset:2048
	global_load_dwordx4 v[120:123], v[76:77], off
	global_load_dwordx4 v[124:127], v[70:71], off offset:3072
	s_lshl_b64 s[30:31], s[4:5], 11
	s_ashr_i32 s23, s22, 31
	s_add_i32 s71, s71, s33
	s_waitcnt vmcnt(15)
	v_mul_f32_e32 v44, v29, v29
	v_mul_f32_e32 v46, v31, v31
	s_waitcnt vmcnt(14)
	v_mul_f32_e32 v47, v25, v25
	v_mul_f32_e32 v52, v27, v27
	s_waitcnt vmcnt(13)
	v_mul_f32_e32 v53, v21, v21
	v_mul_f32_e32 v64, v23, v23
	v_fmac_f32_e32 v44, v28, v28
	v_fmac_f32_e32 v46, v30, v30
	v_fmac_f32_e32 v47, v24, v24
	v_fmac_f32_e32 v52, v26, v26
	s_waitcnt vmcnt(12)
	v_mul_f32_e32 v77, v17, v17
	v_mul_f32_e32 v78, v19, v19
	v_fmac_f32_e32 v53, v20, v20
	v_fmac_f32_e32 v64, v22, v22
	v_add_f32_e32 v44, v44, v46
	v_add_f32_e32 v46, v47, v52
	v_fmac_f32_e32 v77, v16, v16
	v_fmac_f32_e32 v78, v18, v18
	v_add_f32_e32 v47, v53, v64
	v_add_f32_e32 v44, v44, v46
	v_add_f32_e32 v52, v77, v78
	v_add_f32_e32 v44, v44, v47
	v_add_f32_e32 v44, v44, v52
	s_nop 0
	s_nop 0
	v_add_f32_dpp v44, v44, v44 quad_perm:[1,0,3,2] row_mask:0xf bank_mask:0xf bound_ctrl:1
	s_nop 1
	v_add_f32_dpp v44, v44, v44 quad_perm:[2,3,0,1] row_mask:0xf bank_mask:0xf bound_ctrl:1
	s_nop 1
	v_add_f32_dpp v44, v44, v44 row_half_mirror row_mask:0xf bank_mask:0xf bound_ctrl:1
	s_nop 1
	v_add_f32_dpp v44, v44, v44 row_mirror row_mask:0xf bank_mask:0xf bound_ctrl:1
	v_mov_b32_e32 v46, v44
	s_nop 1
	v_permlane16_swap_b32_e32 v44, v46
	v_add_f32_e32 v44, v44, v46
	v_mov_b32_e32 v46, v44
	s_nop 1
	v_permlane32_swap_b32_e32 v44, v46
	v_add_f32_e32 v44, v44, v46
	v_fmamk_f32 v44, v44, 0x3a800000, v72
	v_mul_f32_e32 v46, 0x4f800000, v44
	v_cmp_gt_f32_e64 s[4:5], s29, v44
	s_nop 1
	v_cndmask_b32_e64 v44, v44, v46, s[4:5]
	v_sqrt_f32_e32 v46, v44
	s_nop 0
	v_add_u32_e32 v45, -1, v46
	v_add_u32_e32 v47, 1, v46
	v_fma_f32 v52, -v45, v46, v44
	v_fma_f32 v53, -v47, v46, v44
	v_cmp_ge_f32_e32 vcc, 0, v52
	s_nop 1
	v_cndmask_b32_e32 v45, v46, v45, vcc
	v_cmp_lt_f32_e32 vcc, 0, v53
	s_nop 1
	v_cndmask_b32_e32 v45, v45, v47, vcc
	v_mul_f32_e32 v46, 0x37800000, v45
	v_cndmask_b32_e64 v45, v45, v46, s[4:5]
	v_cmp_class_f32_e32 vcc, v44, v73
	s_nop 1
	v_cndmask_b32_e32 v64, v45, v44, vcc
	v_div_scale_f32 v78, s[4:5], v64, v64, 1.0
	v_rcp_f32_e32 v79, v78
	s_nop 0
	s_nop 0
	s_nop 0
	v_div_scale_f32 v74, vcc, 1.0, v64, 1.0
	v_fma_f32 v75, -v78, v79, 1.0
	v_fmac_f32_e32 v79, v75, v79
	v_mul_f32_e32 v75, v74, v79
	v_fma_f32 v80, -v78, v75, v74
	v_fmac_f32_e32 v75, v80, v79
	v_fma_f32 v74, -v78, v75, v74
	v_div_fmas_f32 v74, v74, v79, v75
	v_div_fixup_f32 v64, v74, v64, 1.0
	v_mul_f32_e32 v28, v28, v64
	v_mul_f32_e32 v30, v30, v64
	v_mul_f32_e32 v29, v29, v64
	v_mul_f32_e32 v31, v31, v64
	v_mul_f32_e32 v86, v16, v64
	v_mul_f32_e32 v88, v18, v64
	v_mul_f32_e32 v16, v0, v28
	v_mul_f32_e32 v18, v2, v30
	v_mul_f32_e32 v78, v24, v64
	v_mul_f32_e32 v79, v25, v64
	v_mul_f32_e32 v80, v26, v64
	v_mul_f32_e32 v81, v27, v64
	v_mul_f32_e32 v82, v20, v64
	v_mul_f32_e32 v83, v21, v64
	v_mul_f32_e32 v84, v22, v64
	v_mul_f32_e32 v85, v23, v64
	v_mul_f32_e32 v87, v17, v64
	v_mul_f32_e32 v64, v19, v64
	v_mul_f32_e32 v17, v1, v29
	v_mul_f32_e32 v19, v3, v31
	v_bfe_u32 v20, v16, 16, 1
	v_bfe_u32 v22, v18, 16, 1
	v_bfe_u32 v21, v17, 16, 1
	v_bfe_u32 v23, v19, 16, 1
	v_add3_u32 v16, v16, v20, s48
	v_add3_u32 v18, v18, v22, s48
	v_add3_u32 v17, v17, v21, s48
	v_add3_u32 v19, v19, v23, s48
	v_lshrrev_b32_e32 v16, 16, v16
	v_lshrrev_b32_e32 v18, 16, v18
	v_and_or_b32 v74, v17, s49, v16
	v_and_or_b32 v75, v19, s49, v18
	s_nop 0
	s_nop 0
	s_nop 0
	s_nop 0
	v_lshl_add_u64 v[70:71], v[68:69], 0, s[30:31]
	global_store_dwordx2 v[70:71], v[74:75], off
	v_mul_f32_e32 v74, v4, v78
	v_bfe_u32 v75, v74, 16, 1
	v_add3_u32 v74, v74, v75, s48
	v_mul_f32_e32 v75, v5, v79
	v_bfe_u32 v76, v75, 16, 1
	v_add3_u32 v75, v75, v76, s48
	v_mul_f32_e32 v76, v6, v80
	v_bfe_u32 v77, v76, 16, 1
	v_add3_u32 v76, v76, v77, s48
	v_mul_f32_e32 v77, v7, v81
	v_bfe_u32 v78, v77, 16, 1
	v_lshrrev_b32_e32 v74, 16, v74
	v_add3_u32 v77, v77, v78, s48
	v_and_or_b32 v74, v75, s49, v74
	v_lshrrev_b32_e32 v75, 16, v76
	v_and_or_b32 v75, v77, s49, v75
	global_store_dwordx2 v[70:71], v[74:75], off offset:512
	v_mul_f32_e32 v74, v8, v82
	v_bfe_u32 v75, v74, 16, 1
	v_add3_u32 v74, v74, v75, s48
	v_mul_f32_e32 v75, v9, v83
	v_bfe_u32 v76, v75, 16, 1
	v_add3_u32 v75, v75, v76, s48
	v_mul_f32_e32 v76, v10, v84
	v_bfe_u32 v77, v76, 16, 1
	v_add3_u32 v76, v76, v77, s48
	v_mul_f32_e32 v77, v11, v85
	v_bfe_u32 v78, v77, 16, 1
	v_add3_u32 v77, v77, v78, s48
	s_waitcnt vmcnt(9)
	v_mul_f32_e32 v78, v61, v61
	v_mul_f32_e32 v79, v63, v63
	v_fmac_f32_e32 v78, v60, v60
	v_fmac_f32_e32 v79, v62, v62
	v_add_f32_e32 v78, v78, v79
	v_mul_f32_e32 v79, v49, v49
	v_mul_f32_e32 v80, v51, v51
	v_fmac_f32_e32 v79, v48, v48
	v_fmac_f32_e32 v80, v50, v50
	v_add_f32_e32 v79, v79, v80
	v_add_f32_e32 v78, v78, v79
	v_mul_f32_e32 v79, v37, v37
	v_mul_f32_e32 v80, v39, v39
	v_fmac_f32_e32 v79, v36, v36
	v_fmac_f32_e32 v80, v38, v38
	v_add_f32_e32 v79, v79, v80
	v_add_f32_e32 v78, v78, v79
	s_waitcnt vmcnt(8)
	v_mul_f32_e32 v79, v57, v57
	v_mul_f32_e32 v80, v59, v59
	v_fmac_f32_e32 v79, v56, v56
	v_fmac_f32_e32 v80, v58, v58
	v_add_f32_e32 v79, v79, v80
	v_add_f32_e32 v78, v78, v79
	v_lshrrev_b32_e32 v74, 16, v74
	v_and_or_b32 v74, v75, s49, v74
	v_add_f32_dpp v78, v78, v78 quad_perm:[1,0,3,2] row_mask:0xf bank_mask:0xf bound_ctrl:1
	v_lshrrev_b32_e32 v75, 16, v76
	v_and_or_b32 v75, v77, s49, v75
	v_add_f32_dpp v78, v78, v78 quad_perm:[2,3,0,1] row_mask:0xf bank_mask:0xf bound_ctrl:1
	global_store_dwordx2 v[70:71], v[74:75], off offset:1024
	v_mul_f32_e32 v74, v12, v86
	v_add_f32_dpp v78, v78, v78 row_half_mirror row_mask:0xf bank_mask:0xf bound_ctrl:1
	v_bfe_u32 v75, v74, 16, 1
	v_add3_u32 v74, v74, v75, s48
	v_add_f32_dpp v78, v78, v78 row_mirror row_mask:0xf bank_mask:0xf bound_ctrl:1
	v_mov_b32_e32 v79, v78
	s_nop 1
	v_permlane16_swap_b32_e32 v78, v79
	v_add_f32_e32 v78, v78, v79
	v_mov_b32_e32 v79, v78
	s_nop 1
	v_permlane32_swap_b32_e32 v78, v79
	v_add_f32_e32 v78, v78, v79
	v_fmamk_f32 v78, v78, 0x3a800000, v72
	v_mul_f32_e32 v79, 0x4f800000, v78
	v_cmp_gt_f32_e32 vcc, s29, v78
	v_mul_f32_e32 v75, v13, v87
	v_bfe_u32 v76, v75, 16, 1
	v_cndmask_b32_e32 v78, v78, v79, vcc
	v_sqrt_f32_e32 v79, v78
	v_add3_u32 v75, v75, v76, s48
	v_mul_f32_e32 v76, v14, v88
	v_bfe_u32 v77, v76, 16, 1
	v_mul_f32_e32 v64, v15, v64
	v_lshrrev_b32_e32 v74, 16, v74
	v_add3_u32 v76, v76, v77, s48
	v_bfe_u32 v77, v64, 16, 1
	v_and_or_b32 v74, v75, s49, v74
	v_add_u32_e32 v75, -1, v79
	v_add3_u32 v64, v64, v77, s48
	v_fma_f32 v77, -v75, v79, v78
	v_cmp_ge_f32_e64 s[4:5], 0, v77
	v_add_u32_e32 v77, 1, v79
	s_nop 0
	v_cndmask_b32_e64 v75, v79, v75, s[4:5]
	v_fma_f32 v79, -v77, v79, v78
	v_cmp_lt_f32_e64 s[4:5], 0, v79
	s_nop 1
	v_cndmask_b32_e64 v75, v75, v77, s[4:5]
	v_mul_f32_e32 v77, 0x37800000, v75
	v_cndmask_b32_e32 v75, v75, v77, vcc
	v_cmp_class_f32_e32 vcc, v78, v73
	s_nop 1
	v_cndmask_b32_e32 v77, v75, v78, vcc
	v_div_scale_f32 v78, s[4:5], v77, v77, 1.0
	v_rcp_f32_e32 v79, v78
	v_lshrrev_b32_e32 v75, 16, v76
	v_and_or_b32 v75, v64, s49, v75
	global_store_dwordx2 v[70:71], v[74:75], off offset:1536
	v_fma_f32 v64, -v78, v79, 1.0
	v_fmac_f32_e32 v79, v64, v79
	v_div_scale_f32 v64, vcc, 1.0, v77, 1.0
	v_mul_f32_e32 v70, v64, v79
	v_fma_f32 v71, -v78, v70, v64
	v_fmac_f32_e32 v70, v71, v79
	v_fma_f32 v64, -v78, v70, v64
	v_div_fmas_f32 v64, v64, v79, v70
	v_div_fixup_f32 v64, v64, v77, 1.0
	v_mul_f32_e32 v60, v60, v64
	v_mul_f32_e32 v70, v48, v64
	v_mul_f32_e32 v48, v0, v60
	v_mul_f32_e32 v61, v61, v64
	v_mul_f32_e32 v71, v49, v64
	v_bfe_u32 v49, v48, 16, 1
	v_add3_u32 v48, v48, v49, s48
	v_mul_f32_e32 v49, v1, v61
	v_mul_f32_e32 v62, v62, v64
	v_mul_f32_e32 v74, v50, v64
	v_bfe_u32 v50, v49, 16, 1
	v_add3_u32 v49, v49, v50, s48
	v_mul_f32_e32 v50, v2, v62
	v_mul_f32_e32 v63, v63, v64
	v_mul_f32_e32 v75, v51, v64
	v_bfe_u32 v51, v50, 16, 1
	v_add3_u32 v50, v50, v51, s48
	v_mul_f32_e32 v51, v3, v63
	v_bfe_u32 v60, v51, 16, 1
	v_lshrrev_b32_e32 v48, 16, v48
	v_add3_u32 v51, v51, v60, s48
	v_and_or_b32 v48, v49, s49, v48
	v_lshrrev_b32_e32 v49, 16, v50
	s_lshl_b64 s[4:5], s[22:23], 11
	v_and_or_b32 v49, v51, s49, v49
	v_lshl_add_u64 v[50:51], v[68:69], 0, s[4:5]
	global_store_dwordx2 v[50:51], v[48:49], off
	v_mul_f32_e32 v48, v4, v70
	v_bfe_u32 v49, v48, 16, 1
	v_add3_u32 v48, v48, v49, s48
	v_mul_f32_e32 v49, v5, v71
	v_bfe_u32 v60, v49, 16, 1
	v_add3_u32 v49, v49, v60, s48
	v_mul_f32_e32 v60, v6, v74
	v_bfe_u32 v61, v60, 16, 1
	v_add3_u32 v60, v60, v61, s48
	v_mul_f32_e32 v61, v7, v75
	v_bfe_u32 v62, v61, 16, 1
	v_lshrrev_b32_e32 v48, 16, v48
	v_add3_u32 v61, v61, v62, s48
	v_and_or_b32 v48, v49, s49, v48
	v_lshrrev_b32_e32 v49, 16, v60
	v_mul_f32_e32 v36, v36, v64
	v_and_or_b32 v49, v61, s49, v49
	v_mul_f32_e32 v36, v8, v36
	v_mul_f32_e32 v37, v37, v64
	global_store_dwordx2 v[50:51], v[48:49], off offset:512
	v_mul_f32_e32 v37, v9, v37
	v_bfe_u32 v48, v36, 16, 1
	v_add3_u32 v36, v36, v48, s48
	v_bfe_u32 v48, v37, 16, 1
	v_lshrrev_b32_e32 v36, 16, v36
	v_add3_u32 v37, v37, v48, s48
	v_and_or_b32 v36, v37, s49, v36
	v_mul_f32_e32 v37, v38, v64
	v_mul_f32_e32 v37, v10, v37
	v_mul_f32_e32 v38, v39, v64
	v_mul_f32_e32 v38, v11, v38
	v_bfe_u32 v39, v37, 16, 1
	v_add3_u32 v37, v37, v39, s48
	v_bfe_u32 v39, v38, 16, 1
	v_lshrrev_b32_e32 v37, 16, v37
	v_add3_u32 v38, v38, v39, s48
	s_waitcnt vmcnt(11)
	v_mul_f32_e32 v48, v105, v105
	v_mul_f32_e32 v49, v107, v107
	v_and_or_b32 v37, v38, s49, v37
	v_fmac_f32_e32 v48, v104, v104
	v_fmac_f32_e32 v49, v106, v106
	global_store_dwordx2 v[50:51], v[36:37], off offset:1024
	v_mul_f32_e32 v36, v56, v64
	v_add_f32_e32 v48, v48, v49
	v_mul_f32_e32 v49, v41, v41
	v_mul_f32_e32 v56, v43, v43
	v_fmac_f32_e32 v49, v40, v40
	v_fmac_f32_e32 v56, v42, v42
	v_add_f32_e32 v49, v49, v56
	v_add_f32_e32 v48, v48, v49
	v_mul_f32_e32 v49, v33, v33
	v_mul_f32_e32 v56, v35, v35
	v_fmac_f32_e32 v49, v32, v32
	v_fmac_f32_e32 v56, v34, v34
	v_add_f32_e32 v49, v49, v56
	v_add_f32_e32 v48, v48, v49
	s_waitcnt vmcnt(11)
	v_mul_f32_e32 v49, v109, v109
	v_mul_f32_e32 v56, v111, v111
	v_fmac_f32_e32 v49, v108, v108
	v_fmac_f32_e32 v56, v110, v110
	v_add_f32_e32 v49, v49, v56
	v_add_f32_e32 v48, v48, v49
	v_mul_f32_e32 v37, v57, v64
	v_mul_f32_e32 v36, v12, v36
	v_add_f32_dpp v48, v48, v48 quad_perm:[1,0,3,2] row_mask:0xf bank_mask:0xf bound_ctrl:1
	v_mul_f32_e32 v37, v13, v37
	v_bfe_u32 v38, v36, 16, 1
	v_add_f32_dpp v48, v48, v48 quad_perm:[2,3,0,1] row_mask:0xf bank_mask:0xf bound_ctrl:1
	v_add3_u32 v36, v36, v38, s48
	v_bfe_u32 v38, v37, 16, 1
	v_add_f32_dpp v48, v48, v48 row_half_mirror row_mask:0xf bank_mask:0xf bound_ctrl:1
	v_lshrrev_b32_e32 v36, 16, v36
	v_add3_u32 v37, v37, v38, s48
	v_add_f32_dpp v48, v48, v48 row_mirror row_mask:0xf bank_mask:0xf bound_ctrl:1
	v_mov_b32_e32 v49, v48
	s_nop 1
	v_permlane16_swap_b32_e32 v48, v49
	v_add_f32_e32 v48, v48, v49
	v_mov_b32_e32 v49, v48
	s_nop 1
	v_permlane32_swap_b32_e32 v48, v49
	v_add_f32_e32 v48, v48, v49
	v_fmamk_f32 v48, v48, 0x3a800000, v72
	v_mul_f32_e32 v49, 0x4f800000, v48
	v_cmp_gt_f32_e32 vcc, s29, v48
	v_and_or_b32 v36, v37, s49, v36
	v_mul_f32_e32 v37, v58, v64
	v_cndmask_b32_e32 v48, v48, v49, vcc
	v_sqrt_f32_e32 v49, v48
	v_mul_f32_e32 v37, v14, v37
	v_mul_f32_e32 v38, v59, v64
	v_mul_f32_e32 v38, v15, v38
	v_add_u32_e32 v56, -1, v49
	v_fma_f32 v57, -v56, v49, v48
	v_cmp_ge_f32_e64 s[4:5], 0, v57
	v_add_u32_e32 v57, 1, v49
	v_bfe_u32 v39, v37, 16, 1
	v_cndmask_b32_e64 v56, v49, v56, s[4:5]
	v_fma_f32 v49, -v57, v49, v48
	v_cmp_lt_f32_e64 s[4:5], 0, v49
	v_add3_u32 v37, v37, v39, s48
	v_bfe_u32 v39, v38, 16, 1
	v_cndmask_b32_e64 v49, v56, v57, s[4:5]
	v_mul_f32_e32 v56, 0x37800000, v49
	v_cndmask_b32_e32 v49, v49, v56, vcc
	v_cmp_class_f32_e32 vcc, v48, v73
	v_lshrrev_b32_e32 v37, 16, v37
	v_add3_u32 v38, v38, v39, s48
	v_cndmask_b32_e32 v48, v49, v48, vcc
	v_div_scale_f32 v49, s[4:5], v48, v48, 1.0
	v_rcp_f32_e32 v56, v49
	v_and_or_b32 v37, v38, s49, v37
	global_store_dwordx2 v[50:51], v[36:37], off offset:1536
	s_add_i32 s4, s22, 1
	v_fma_f32 v36, -v49, v56, 1.0
	v_fmac_f32_e32 v56, v36, v56
	v_div_scale_f32 v36, vcc, 1.0, v48, 1.0
	v_mul_f32_e32 v37, v36, v56
	v_fma_f32 v38, -v49, v37, v36
	v_fmac_f32_e32 v37, v38, v56
	v_fma_f32 v36, -v49, v37, v36
	v_div_fmas_f32 v36, v36, v56, v37
	v_div_fixup_f32 v48, v36, v48, 1.0
	v_mul_f32_e32 v38, v104, v48
	v_mul_f32_e32 v38, v0, v38
	v_mul_f32_e32 v39, v105, v48
	v_mul_f32_e32 v39, v1, v39
	v_bfe_u32 v49, v38, 16, 1
	v_add3_u32 v38, v38, v49, s48
	v_bfe_u32 v49, v39, 16, 1
	v_lshrrev_b32_e32 v38, 16, v38
	v_add3_u32 v39, v39, v49, s48
	v_and_or_b32 v38, v39, s49, v38
	v_mul_f32_e32 v39, v106, v48
	v_mul_f32_e32 v39, v2, v39
	v_mul_f32_e32 v49, v107, v48
	v_mul_f32_e32 v49, v3, v49
	v_bfe_u32 v50, v39, 16, 1
	s_ashr_i32 s5, s4, 31
	v_add3_u32 v39, v39, v50, s48
	v_bfe_u32 v50, v49, 16, 1
	s_lshl_b64 s[4:5], s[4:5], 11
	v_lshrrev_b32_e32 v39, 16, v39
	v_add3_u32 v49, v49, v50, s48
	v_lshl_add_u64 v[36:37], v[68:69], 0, s[4:5]
	v_and_or_b32 v39, v49, s49, v39
	global_store_dwordx2 v[36:37], v[38:39], off
	v_mul_f32_e32 v38, v40, v48
	v_mul_f32_e32 v38, v4, v38
	v_mul_f32_e32 v39, v41, v48
	v_mul_f32_e32 v39, v5, v39
	v_bfe_u32 v40, v38, 16, 1
	v_add3_u32 v38, v38, v40, s48
	v_bfe_u32 v40, v39, 16, 1
	v_lshrrev_b32_e32 v38, 16, v38
	v_add3_u32 v39, v39, v40, s48
	v_and_or_b32 v38, v39, s49, v38
	v_mul_f32_e32 v39, v42, v48
	v_mul_f32_e32 v39, v6, v39
	v_mul_f32_e32 v40, v43, v48
	v_mul_f32_e32 v40, v7, v40
	v_bfe_u32 v41, v39, 16, 1
	v_add3_u32 v39, v39, v41, s48
	v_bfe_u32 v41, v40, 16, 1
	v_lshrrev_b32_e32 v39, 16, v39
	v_add3_u32 v40, v40, v41, s48
	v_mul_f32_e32 v32, v32, v48
	v_and_or_b32 v39, v40, s49, v39
	v_mul_f32_e32 v32, v8, v32
	v_mul_f32_e32 v33, v33, v48
	global_store_dwordx2 v[36:37], v[38:39], off offset:512
	v_mul_f32_e32 v33, v9, v33
	v_bfe_u32 v38, v32, 16, 1
	v_add3_u32 v32, v32, v38, s48
	v_bfe_u32 v38, v33, 16, 1
	v_add3_u32 v33, v33, v38, s48
	s_waitcnt vmcnt(11)
	v_mul_f32_e32 v38, v121, v121
	v_mul_f32_e32 v39, v123, v123
	v_fmac_f32_e32 v38, v120, v120
	v_fmac_f32_e32 v39, v122, v122
	v_add_f32_e32 v38, v38, v39
	v_mul_f32_e32 v39, v113, v113
	v_mul_f32_e32 v40, v115, v115
	v_fmac_f32_e32 v39, v112, v112
	v_fmac_f32_e32 v40, v114, v114
	v_add_f32_e32 v39, v39, v40
	v_add_f32_e32 v38, v38, v39
	v_mul_f32_e32 v39, v117, v117
	v_mul_f32_e32 v40, v119, v119
	v_fmac_f32_e32 v39, v116, v116
	v_fmac_f32_e32 v40, v118, v118
	v_add_f32_e32 v39, v39, v40
	v_add_f32_e32 v38, v38, v39
	s_waitcnt vmcnt(10)
	v_mul_f32_e32 v39, v125, v125
	v_mul_f32_e32 v40, v127, v127
	v_fmac_f32_e32 v39, v124, v124
	v_fmac_f32_e32 v40, v126, v126
	v_add_f32_e32 v39, v39, v40
	v_add_f32_e32 v38, v38, v39
	v_lshrrev_b32_e32 v32, 16, v32
	v_and_or_b32 v32, v33, s49, v32
	v_add_f32_dpp v38, v38, v38 quad_perm:[1,0,3,2] row_mask:0xf bank_mask:0xf bound_ctrl:1
	v_mul_f32_e32 v33, v34, v48
	v_mul_f32_e32 v33, v10, v33
	v_add_f32_dpp v38, v38, v38 quad_perm:[2,3,0,1] row_mask:0xf bank_mask:0xf bound_ctrl:1
	v_mul_f32_e32 v34, v35, v48
	v_mul_f32_e32 v34, v11, v34
	v_add_f32_dpp v38, v38, v38 row_half_mirror row_mask:0xf bank_mask:0xf bound_ctrl:1
	v_bfe_u32 v35, v33, 16, 1
	v_add3_u32 v33, v33, v35, s48
	v_add_f32_dpp v38, v38, v38 row_mirror row_mask:0xf bank_mask:0xf bound_ctrl:1
	v_mov_b32_e32 v39, v38
	s_nop 1
	v_permlane16_swap_b32_e32 v38, v39
	v_add_f32_e32 v38, v38, v39
	v_mov_b32_e32 v39, v38
	s_nop 1
	v_permlane32_swap_b32_e32 v38, v39
	v_add_f32_e32 v38, v38, v39
	v_fmamk_f32 v38, v38, 0x3a800000, v72
	v_mul_f32_e32 v39, 0x4f800000, v38
	v_cmp_gt_f32_e32 vcc, s29, v38
	v_bfe_u32 v35, v34, 16, 1
	v_lshrrev_b32_e32 v33, 16, v33
	v_cndmask_b32_e32 v38, v38, v39, vcc
	v_sqrt_f32_e32 v39, v38
	v_add3_u32 v34, v34, v35, s48
	v_and_or_b32 v33, v34, s49, v33
	global_store_dwordx2 v[36:37], v[32:33], off offset:1024
	v_add_u32_e32 v40, -1, v39
	v_fma_f32 v41, -v40, v39, v38
	v_cmp_ge_f32_e64 s[4:5], 0, v41
	v_add_u32_e32 v41, 1, v39
	v_mul_f32_e32 v32, v108, v48
	v_cndmask_b32_e64 v40, v39, v40, s[4:5]
	v_fma_f32 v39, -v41, v39, v38
	v_mul_f32_e32 v32, v12, v32
	v_mul_f32_e32 v33, v109, v48
	v_cmp_lt_f32_e64 s[4:5], 0, v39
	v_mul_f32_e32 v33, v13, v33
	v_bfe_u32 v34, v32, 16, 1
	v_cndmask_b32_e64 v39, v40, v41, s[4:5]
	v_add3_u32 v32, v32, v34, s48
	v_bfe_u32 v34, v33, 16, 1
	v_mul_f32_e32 v40, 0x37800000, v39
	v_lshrrev_b32_e32 v32, 16, v32
	v_add3_u32 v33, v33, v34, s48
	v_cndmask_b32_e32 v39, v39, v40, vcc
	v_cmp_class_f32_e32 vcc, v38, v73
	v_and_or_b32 v32, v33, s49, v32
	v_mul_f32_e32 v33, v110, v48
	v_cndmask_b32_e32 v38, v39, v38, vcc
	v_mul_f32_e32 v33, v14, v33
	v_mul_f32_e32 v34, v111, v48
	v_div_scale_f32 v39, s[4:5], v38, v38, 1.0
	v_mul_f32_e32 v34, v15, v34
	v_bfe_u32 v35, v33, 16, 1
	v_rcp_f32_e32 v40, v39
	v_add3_u32 v33, v33, v35, s48
	v_bfe_u32 v35, v34, 16, 1
	v_lshrrev_b32_e32 v33, 16, v33
	v_add3_u32 v34, v34, v35, s48
	v_and_or_b32 v33, v34, s49, v33
	global_store_dwordx2 v[36:37], v[32:33], off offset:1536
	v_fma_f32 v32, -v39, v40, 1.0
	v_fmac_f32_e32 v40, v32, v40
	v_div_scale_f32 v32, vcc, 1.0, v38, 1.0
	v_mul_f32_e32 v33, v32, v40
	v_fma_f32 v34, -v39, v33, v32
	v_fmac_f32_e32 v33, v34, v40
	v_fma_f32 v32, -v39, v33, v32
	v_div_fmas_f32 v32, v32, v40, v33
	v_div_fixup_f32 v34, v32, v38, 1.0
	v_mul_f32_e32 v28, v120, v34
	v_mul_f32_e32 v28, v0, v28
	v_mul_f32_e32 v29, v121, v34
	v_mul_f32_e32 v29, v1, v29
	v_bfe_u32 v35, v28, 16, 1
	v_add3_u32 v28, v28, v35, s48
	v_bfe_u32 v35, v29, 16, 1
	v_lshrrev_b32_e32 v28, 16, v28
	v_add3_u32 v29, v29, v35, s48
	v_and_or_b32 v28, v29, s49, v28
	v_mul_f32_e32 v29, v122, v34
	v_mul_f32_e32 v29, v2, v29
	v_mul_f32_e32 v30, v123, v34
	s_add_i32 s4, s22, 2
	v_mul_f32_e32 v30, v3, v30
	v_bfe_u32 v31, v29, 16, 1
	s_ashr_i32 s5, s4, 31
	v_add3_u32 v29, v29, v31, s48
	v_bfe_u32 v31, v30, 16, 1
	s_lshl_b64 s[4:5], s[4:5], 11
	v_lshrrev_b32_e32 v29, 16, v29
	v_add3_u32 v30, v30, v31, s48
	v_mul_f32_e32 v24, v112, v34
	v_lshl_add_u64 v[32:33], v[68:69], 0, s[4:5]
	v_and_or_b32 v29, v30, s49, v29
	v_mul_f32_e32 v24, v4, v24
	v_mul_f32_e32 v25, v113, v34
	global_store_dwordx2 v[32:33], v[28:29], off
	v_mul_f32_e32 v25, v5, v25
	v_bfe_u32 v28, v24, 16, 1
	v_add3_u32 v24, v24, v28, s48
	v_bfe_u32 v28, v25, 16, 1
	v_lshrrev_b32_e32 v24, 16, v24
	v_add3_u32 v25, v25, v28, s48
	v_and_or_b32 v24, v25, s49, v24
	v_mul_f32_e32 v25, v114, v34
	v_mul_f32_e32 v25, v6, v25
	v_mul_f32_e32 v26, v115, v34
	v_mul_f32_e32 v26, v7, v26
	v_bfe_u32 v27, v25, 16, 1
	v_add3_u32 v25, v25, v27, s48
	v_bfe_u32 v27, v26, 16, 1
	v_lshrrev_b32_e32 v25, 16, v25
	v_add3_u32 v26, v26, v27, s48
	v_mul_f32_e32 v20, v116, v34
	v_and_or_b32 v25, v26, s49, v25
	v_mul_f32_e32 v20, v8, v20
	v_mul_f32_e32 v21, v117, v34
	global_store_dwordx2 v[32:33], v[24:25], off offset:512
	v_mul_f32_e32 v21, v9, v21
	v_bfe_u32 v24, v20, 16, 1
	v_add3_u32 v20, v20, v24, s48
	v_bfe_u32 v24, v21, 16, 1
	v_lshrrev_b32_e32 v20, 16, v20
	v_add3_u32 v21, v21, v24, s48
	v_and_or_b32 v20, v21, s49, v20
	v_mul_f32_e32 v21, v118, v34
	v_mul_f32_e32 v21, v10, v21
	v_mul_f32_e32 v22, v119, v34
	v_mul_f32_e32 v22, v11, v22
	v_bfe_u32 v23, v21, 16, 1
	v_add3_u32 v21, v21, v23, s48
	v_bfe_u32 v23, v22, 16, 1
	v_lshrrev_b32_e32 v21, 16, v21
	v_add3_u32 v22, v22, v23, s48
	v_mul_f32_e32 v16, v124, v34
	v_and_or_b32 v21, v22, s49, v21
	v_mul_f32_e32 v16, v12, v16
	v_mul_f32_e32 v17, v125, v34
	global_store_dwordx2 v[32:33], v[20:21], off offset:1024
	v_mul_f32_e32 v17, v13, v17
	v_bfe_u32 v20, v16, 16, 1
	v_add3_u32 v16, v16, v20, s48
	v_bfe_u32 v20, v17, 16, 1
	v_lshrrev_b32_e32 v16, 16, v16
	v_add3_u32 v17, v17, v20, s48
	v_and_or_b32 v16, v17, s49, v16
	v_mul_f32_e32 v17, v126, v34
	v_mul_f32_e32 v17, v14, v17
	v_mul_f32_e32 v18, v127, v34
	v_mul_f32_e32 v18, v15, v18
	v_bfe_u32 v19, v17, 16, 1
	v_add3_u32 v17, v17, v19, s48
	v_bfe_u32 v19, v18, 16, 1
	v_lshrrev_b32_e32 v17, 16, v17
	v_add3_u32 v18, v18, v19, s48
	s_add_i32 s22, s22, s91
	v_and_or_b32 v17, v18, s49, v17
	s_cmpk_lt_i32 s71, 0x1100
	global_store_dwordx2 v[32:33], v[16:17], off offset:1536
	s_cbranch_scc0 .LBB0_20
